# attention loops trimmed: persistent negated-max splats (MLA), merged lgkmcnt/vmcnt waits, fewer SALU in prefetch pointer update
# speedup vs baseline: 1.0578x; 1.0061x over previous
; template <int DK>
; DEVI void attn_tile(const char* kb, const char* vb, const bool first, const bf16x8 (&qf)[2][DK / 32], f32x4 (&o)[2][4],
;                     float (&mrun)[2], float (&lsum)[2], const int l15, const int quad) {
;     ...
;   f32x4 s[2][4];
; #pragma unroll
;   for (int qt = 0; qt < 2; ++qt)
; #pragma unroll
;     for (int ks = 0; ks < 4; ++ks) { const float nm = -mrun[qt]; s[qt][ks] = f32x4{nm, nm, nm, nm}; }
; #pragma unroll
;   for (int ks = 0; ks < 4; ++ks)
; #pragma unroll
;     for (int kk = 0; kk < NKK; ++kk) {
;       bf16x8 kf = *reinterpret_cast<const bf16x8*>(kb + (ks * 16 + l15) * KSTR + (kk * 32 + quad * 8) * 2);
;       s[0][ks] = mfma16(kf, qf[0][kk], s[0][ks]);
;       s[1][ks] = mfma16(kf, qf[1][kk], s[1][ks]);
;     }
;   bf16x8 pf[2][2];
; #pragma unroll
;   for (int qt = 0; qt < 2; ++qt) {
;     float mx = fmaxf(fmaxf(s[qt][0][0], s[qt][0][1]), fmaxf(s[qt][0][2], s[qt][0][3]));
; #pragma unroll
;     for (int ks = 1; ks < 4; ++ks) mx = fmaxf(mx, fmaxf(fmaxf(s[qt][ks][0], s[qt][ks][1]), fmaxf(s[qt][ks][2], s[qt][ks][3])));
;     if (__any(first || (mx > 8.f))) {
;       float rm = fmaxf(mx, __shfl_xor(mx, 16));
;       rm = fmaxf(rm, __shfl_xor(rm, 32));
;       const float delta = first ? rm : fmaxf(rm, 0.f);
;       const float alpha = first ? 1.f : ex2(-delta);
;       mrun[qt] += delta;
;       lsum[qt] *= alpha;
; #pragma unroll
;       for (int ks = 0; ks < 4; ++ks)
; #pragma unroll
;         for (int j = 0; j < 4; ++j) s[qt][ks][j] -= delta;
; #pragma unroll
;       for (int dd = 0; dd < 4; ++dd)
; #pragma unroll
;         for (int j = 0; j < 4; ++j) o[qt][dd][j] *= alpha;
;     }
;     float ps = 0.f;
; #pragma unroll
;     for (int ks = 0; ks < 4; ++ks)
; #pragma unroll
;       for (int j = 0; j < 4; ++j) { float pv = ex2(s[qt][ks][j]); s[qt][ks][j] = pv; ps += pv; }
;     lsum[qt] += ps;
; #pragma unroll
;     for (int k2 = 0; k2 < 2; ++k2) {
;       u32x4 wv;
;       wv[0] = pack2(s[qt][2 * k2][0], s[qt][2 * k2][1]);
;       wv[1] = pack2(s[qt][2 * k2][2], s[qt][2 * k2][3]);
;       wv[2] = pack2(s[qt][2 * k2 + 1][0], s[qt][2 * k2 + 1][1]);
;       wv[3] = pack2(s[qt][2 * k2 + 1][2], s[qt][2 * k2 + 1][3]);
;       pf[qt][k2] = as_bf8(wv);
;     }
;   }
; #pragma unroll
;   for (int dd = 0; dd < 4; ++dd)
; #pragma unroll
;     for (int k2 = 0; k2 < 2; ++k2) {
.Lgqa_loop_g:
	v_add_u32_e32 v211, s18, v168
	ds_read_b128 v[100:103], v211
	ds_read_b128 v[104:107], v211 offset:64
	global_load_dwordx4 v[192:195], v204, s[12:13]
	global_load_dwordx4 v[196:199], v205, s[12:13]
	global_load_dwordx4 v[244:247], v206, s[22:23]
	global_load_dwordx4 v[164:167], v207, s[22:23]
	s_add_i32 s96, s11, 2
	s_cmp_lt_i32 s96, s3
	s_cselect_b32 s96, 0x2000, 0
	s_cselect_b32 s17, 0x80, 0
	s_add_u32 s12, s12, s96
	s_addc_u32 s13, s13, 0
	s_add_u32 s22, s22, s17
	s_addc_u32 s23, s23, 0
	ds_read_b128 v[108:111], v211 offset:2560
	ds_read_b128 v[112:115], v211 offset:2624
	ds_read_b128 v[116:119], v211 offset:5120
	ds_read_b128 v[120:123], v211 offset:5184
	ds_read_b128 v[124:127], v211 offset:7680
	ds_read_b128 v[128:131], v211 offset:7744
	s_waitcnt lgkmcnt(7)
	v_mfma_f32_16x16x32_bf16 v[132:135], v[100:103], v[4:7], v[228:231]
	s_waitcnt lgkmcnt(6)
	v_mfma_f32_16x16x32_bf16 v[132:135], v[104:107], v[12:15], v[132:135]
	s_waitcnt lgkmcnt(4)
	v_mfma_f32_16x16x32_bf16 v[136:139], v[108:111], v[4:7], v[228:231]
	v_mfma_f32_16x16x32_bf16 v[136:139], v[112:115], v[12:15], v[136:139]
	s_waitcnt lgkmcnt(2)
	v_mfma_f32_16x16x32_bf16 v[140:143], v[116:119], v[4:7], v[228:231]
	v_mfma_f32_16x16x32_bf16 v[140:143], v[120:123], v[12:15], v[140:143]
	s_waitcnt lgkmcnt(0)
	v_mfma_f32_16x16x32_bf16 v[144:147], v[124:127], v[4:7], v[228:231]
	v_mfma_f32_16x16x32_bf16 v[144:147], v[128:131], v[12:15], v[144:147]
	v_mfma_f32_16x16x32_bf16 v[212:215], v[100:103], v[8:11], v[236:239]
	v_mfma_f32_16x16x32_bf16 v[212:215], v[104:107], v[16:19], v[212:215]
	v_max3_f32 v153, v132, v133, v134
	v_max3_f32 v154, v135, v136, v137
	v_mfma_f32_16x16x32_bf16 v[216:219], v[108:111], v[8:11], v[236:239]
	v_max3_f32 v155, v138, v139, v140
	v_max3_f32 v156, v141, v142, v143
	v_mfma_f32_16x16x32_bf16 v[216:219], v[112:115], v[16:19], v[216:219]
	s_nop 0
	v_max3_f32 v153, v153, v154, v144
	v_max3_f32 v155, v155, v156, v145
	v_max3_f32 v153, v153, v155, v146
	v_max_f32_e32 v153, v153, v147
	v_cmp_lt_f32_e32 vcc, 0x41000000, v153
	s_cbranch_vccnz .Lgqa_rare0_ga
.Lgqa_join0_ga:
	v_add_u32_e32 v208, s18, v169
	ds_read_b64 v[100:101], v208 offset:0
	ds_read_b64 v[102:103], v208 offset:32
	ds_read_b64 v[104:105], v208 offset:2304
	ds_read_b64 v[106:107], v208 offset:2336
	ds_read_b64 v[108:109], v208 offset:4608
	ds_read_b64 v[110:111], v208 offset:4640
	ds_read_b64 v[112:113], v208 offset:6912
	ds_read_b64 v[114:115], v208 offset:6944
	v_mfma_f32_16x16x32_bf16 v[220:223], v[116:119], v[8:11], v[236:239]
	v_exp_f32_e32 v132, v132
	v_exp_f32_e32 v133, v133
	v_exp_f32_e32 v134, v134
	v_exp_f32_e32 v135, v135
	v_add_f32_e32 v154, v132, v133
	v_exp_f32_e32 v136, v136
	v_add_f32_e32 v155, v134, v135
	v_exp_f32_e32 v137, v137
	v_exp_f32_e32 v138, v138
	v_add_f32_e32 v154, v154, v136
	v_mfma_f32_16x16x32_bf16 v[220:223], v[120:123], v[16:19], v[220:223]
	v_exp_f32_e32 v139, v139
	v_add_f32_e32 v155, v155, v137
	v_exp_f32_e32 v140, v140
	v_add_f32_e32 v154, v154, v138
	v_exp_f32_e32 v141, v141
	v_add_f32_e32 v155, v155, v139
	v_exp_f32_e32 v142, v142
	v_add_f32_e32 v154, v154, v140
	v_exp_f32_e32 v143, v143
	v_add_f32_e32 v155, v155, v141
	v_mfma_f32_16x16x32_bf16 v[224:227], v[124:127], v[8:11], v[236:239]
	v_exp_f32_e32 v144, v144
	v_add_f32_e32 v154, v154, v142
	v_exp_f32_e32 v145, v145
	v_add_f32_e32 v155, v155, v143
	v_exp_f32_e32 v146, v146
	v_add_f32_e32 v154, v154, v144
	v_exp_f32_e32 v147, v147
	v_add_f32_e32 v155, v155, v145
	v_add_f32_e32 v154, v154, v146
	v_add_f32_e32 v155, v155, v147
	v_mfma_f32_16x16x32_bf16 v[224:227], v[128:131], v[16:19], v[224:227]
	v_add_f32_e32 v154, v154, v155
	v_add_f32_e32 v176, v176, v154
	v_cvt_pk_bf16_f32 v228, v132, v133
	v_cvt_pk_bf16_f32 v229, v134, v135
	v_cvt_pk_bf16_f32 v230, v136, v137
	v_cvt_pk_bf16_f32 v231, v138, v139
	v_cvt_pk_bf16_f32 v232, v140, v141
	v_cvt_pk_bf16_f32 v233, v142, v143
	v_cvt_pk_bf16_f32 v234, v144, v145
	v_cvt_pk_bf16_f32 v235, v146, v147
	ds_read_b64 v[116:117], v208 offset:64
	ds_read_b64 v[118:119], v208 offset:96
	ds_read_b64 v[120:121], v208 offset:2368
	ds_read_b64 v[122:123], v208 offset:2400
	ds_read_b64 v[124:125], v208 offset:4672
	ds_read_b64 v[126:127], v208 offset:4704
	ds_read_b64 v[128:129], v208 offset:6976
	ds_read_b64 v[130:131], v208 offset:7008
	v_max3_f32 v153, v212, v213, v214
	v_max3_f32 v154, v215, v216, v217
	v_max3_f32 v155, v218, v219, v220
	v_max3_f32 v156, v221, v222, v223
	s_waitcnt lgkmcnt(12)
	v_mfma_f32_16x16x32_bf16 v[52:55], v[100:103], v[228:231], v[52:55]
	v_max3_f32 v153, v153, v154, v224
	v_max3_f32 v155, v155, v156, v225
	v_mfma_f32_16x16x32_bf16 v[56:59], v[104:107], v[228:231], v[56:59]
	v_max3_f32 v153, v153, v155, v226
	v_max_f32_e32 v153, v153, v227
	v_cmp_lt_f32_e32 vcc, 0x41000000, v153
	s_cbranch_vccnz .Lgqa_rare1_ga
; DEVI float ex2(float x) { return __builtin_amdgcn_exp2f(x); }
; template <int DK>
; DEVI void attn_tile(const char* kb, const char* vb, const bool first, const bf16x8 (&qf)[2][DK / 32], f32x4 (&o)[2][4],
;                     float (&mrun)[2], float (&lsum)[2], const int l15, const int quad) {
;     ...
;   for (int qt = 0; qt < 2; ++qt)
; #pragma unroll
;     for (int ks = 0; ks < 4; ++ks) { const float nm = -mrun[qt]; s[qt][ks] = f32x4{nm, nm, nm, nm}; }
; #pragma unroll
;   for (int ks = 0; ks < 4; ++ks)
; #pragma unroll
;     for (int kk = 0; kk < NKK; ++kk) {
;       bf16x8 kf = *reinterpret_cast<const bf16x8*>(kb + (ks * 16 + l15) * KSTR + (kk * 32 + quad * 8) * 2);
;       s[0][ks] = mfma16(kf, qf[0][kk], s[0][ks]);
;       s[1][ks] = mfma16(kf, qf[1][kk], s[1][ks]);
;     }
;   bf16x8 pf[2][2];
; #pragma unroll
;   for (int qt = 0; qt < 2; ++qt) {
;     float mx = fmaxf(fmaxf(s[qt][0][0], s[qt][0][1]), fmaxf(s[qt][0][2], s[qt][0][3]));
; #pragma unroll
;     for (int ks = 1; ks < 4; ++ks) mx = fmaxf(mx, fmaxf(fmaxf(s[qt][ks][0], s[qt][ks][1]), fmaxf(s[qt][ks][2], s[qt][ks][3])));
;     if (__any(first || (mx > 8.f))) {
;       float rm = fmaxf(mx, __shfl_xor(mx, 16));
;       rm = fmaxf(rm, __shfl_xor(rm, 32));
;       const float delta = first ? rm : fmaxf(rm, 0.f);
;       const float alpha = first ? 1.f : ex2(-delta);
;       mrun[qt] += delta;
;       lsum[qt] *= alpha;
; #pragma unroll
;       for (int ks = 0; ks < 4; ++ks)
; #pragma unroll
;         for (int j = 0; j < 4; ++j) s[qt][ks][j] -= delta;
; #pragma unroll
;       for (int dd = 0; dd < 4; ++dd)
; #pragma unroll
;         for (int j = 0; j < 4; ++j) o[qt][dd][j] *= alpha;
;     }
;     float ps = 0.f;
; #pragma unroll
;     for (int ks = 0; ks < 4; ++ks)
; #pragma unroll
;       for (int j = 0; j < 4; ++j) { float pv = ex2(s[qt][ks][j]); s[qt][ks][j] = pv; ps += pv; }
;     lsum[qt] += ps;
; #pragma unroll
;     for (int k2 = 0; k2 < 2; ++k2) {
;       u32x4 wv;
;       wv[0] = pack2(s[qt][2 * k2][0], s[qt][2 * k2][1]);
;       wv[1] = pack2(s[qt][2 * k2][2], s[qt][2 * k2][3]);
;       wv[2] = pack2(s[qt][2 * k2 + 1][0], s[qt][2 * k2 + 1][1]);
;       wv[3] = pack2(s[qt][2 * k2 + 1][2], s[qt][2 * k2 + 1][3]);
;       pf[qt][k2] = as_bf8(wv);
;     }
;   }
; #pragma unroll
;   for (int dd = 0; dd < 4; ++dd)
; #pragma unroll
;     for (int k2 = 0; k2 < 2; ++k2) {
.Lgqa_join1_ga:
	s_waitcnt lgkmcnt(8)
	v_mfma_f32_16x16x32_bf16 v[60:63], v[108:111], v[228:231], v[60:63]
	v_exp_f32_e32 v212, v212
	v_exp_f32_e32 v213, v213
	v_exp_f32_e32 v214, v214
	v_exp_f32_e32 v215, v215
	v_add_f32_e32 v154, v212, v213
	v_exp_f32_e32 v216, v216
	v_mfma_f32_16x16x32_bf16 v[64:67], v[112:115], v[228:231], v[64:67]
	v_add_f32_e32 v155, v214, v215
	v_exp_f32_e32 v217, v217
	v_exp_f32_e32 v218, v218
	v_add_f32_e32 v154, v154, v216
	v_exp_f32_e32 v219, v219
	v_add_f32_e32 v155, v155, v217
	v_exp_f32_e32 v220, v220
	s_waitcnt lgkmcnt(4)
	v_mfma_f32_16x16x32_bf16 v[52:55], v[116:119], v[232:235], v[52:55]
	v_add_f32_e32 v154, v154, v218
	v_exp_f32_e32 v221, v221
	v_add_f32_e32 v155, v155, v219
	v_exp_f32_e32 v222, v222
	v_add_f32_e32 v154, v154, v220
	v_exp_f32_e32 v223, v223
	v_add_f32_e32 v155, v155, v221
	v_mfma_f32_16x16x32_bf16 v[56:59], v[120:123], v[232:235], v[56:59]
	v_exp_f32_e32 v224, v224
	v_add_f32_e32 v154, v154, v222
	v_exp_f32_e32 v225, v225
	v_add_f32_e32 v155, v155, v223
	v_exp_f32_e32 v226, v226
	v_add_f32_e32 v154, v154, v224
	s_waitcnt lgkmcnt(0)
	v_mfma_f32_16x16x32_bf16 v[60:63], v[124:127], v[232:235], v[60:63]
	v_exp_f32_e32 v227, v227
	v_add_f32_e32 v155, v155, v225
	v_add_f32_e32 v154, v154, v226
	v_add_f32_e32 v155, v155, v227
	v_add_f32_e32 v154, v154, v155
	v_add_f32_e32 v175, v175, v154
	v_cvt_pk_bf16_f32 v236, v212, v213
	v_mfma_f32_16x16x32_bf16 v[64:67], v[128:131], v[232:235], v[64:67]
	v_cvt_pk_bf16_f32 v237, v214, v215
	v_cvt_pk_bf16_f32 v238, v216, v217
	v_cvt_pk_bf16_f32 v239, v218, v219
	v_cvt_pk_bf16_f32 v240, v220, v221
	v_cvt_pk_bf16_f32 v241, v222, v223
	v_cvt_pk_bf16_f32 v242, v224, v225
	v_cvt_pk_bf16_f32 v243, v226, v227
	s_nop 0
	v_mfma_f32_16x16x32_bf16 v[36:39], v[100:103], v[236:239], v[36:39]
	v_mfma_f32_16x16x32_bf16 v[40:43], v[104:107], v[236:239], v[40:43]
	v_mfma_f32_16x16x32_bf16 v[44:47], v[108:111], v[236:239], v[44:47]
	v_mfma_f32_16x16x32_bf16 v[48:51], v[112:115], v[236:239], v[48:51]
	v_xor_b32_e32 v228, 0x80000000, v172
	v_mov_b32_e32 v229, v228
	v_mfma_f32_16x16x32_bf16 v[36:39], v[116:119], v[240:243], v[36:39]
	v_mfma_f32_16x16x32_bf16 v[40:43], v[120:123], v[240:243], v[40:43]
	v_mfma_f32_16x16x32_bf16 v[44:47], v[124:127], v[240:243], v[44:47]
	v_mfma_f32_16x16x32_bf16 v[48:51], v[128:131], v[240:243], v[48:51]
	v_mov_b32_e32 v230, v228
	v_mov_b32_e32 v231, v228
	v_xor_b32_e32 v236, 0x80000000, v173
	v_mov_b32_e32 v237, v236
	v_mov_b32_e32 v238, v236
	v_mov_b32_e32 v239, v236
	v_add_u32_e32 v211, s18, v168
	ds_read_b128 v[100:103], v211
	ds_read_b128 v[104:107], v211 offset:64
	ds_read_b128 v[108:111], v211 offset:2560
	ds_read_b128 v[112:115], v211 offset:2624
	ds_read_b128 v[116:119], v211 offset:5120
	ds_read_b128 v[120:123], v211 offset:5184
	ds_read_b128 v[124:127], v211 offset:7680
	ds_read_b128 v[128:131], v211 offset:7744
	s_waitcnt lgkmcnt(7)
	v_mfma_f32_16x16x32_bf16 v[132:135], v[100:103], v[20:23], v[228:231]
	s_waitcnt lgkmcnt(6)
	v_mfma_f32_16x16x32_bf16 v[132:135], v[104:107], v[24:27], v[132:135]
	s_waitcnt lgkmcnt(4)
	v_mfma_f32_16x16x32_bf16 v[136:139], v[108:111], v[20:23], v[228:231]
	v_mfma_f32_16x16x32_bf16 v[136:139], v[112:115], v[24:27], v[136:139]
	s_waitcnt lgkmcnt(2)
	v_mfma_f32_16x16x32_bf16 v[140:143], v[116:119], v[20:23], v[228:231]
	v_mfma_f32_16x16x32_bf16 v[140:143], v[120:123], v[24:27], v[140:143]
	s_waitcnt lgkmcnt(0)
	v_mfma_f32_16x16x32_bf16 v[144:147], v[124:127], v[20:23], v[228:231]
	v_mfma_f32_16x16x32_bf16 v[144:147], v[128:131], v[24:27], v[144:147]
	v_mfma_f32_16x16x32_bf16 v[212:215], v[100:103], v[28:31], v[236:239]
	v_mfma_f32_16x16x32_bf16 v[212:215], v[104:107], v[32:35], v[212:215]
	v_max3_f32 v153, v132, v133, v134
	v_max3_f32 v154, v135, v136, v137
	v_mfma_f32_16x16x32_bf16 v[216:219], v[108:111], v[28:31], v[236:239]
	v_max3_f32 v155, v138, v139, v140
	v_max3_f32 v156, v141, v142, v143
	v_mfma_f32_16x16x32_bf16 v[216:219], v[112:115], v[32:35], v[216:219]
	s_nop 0
	v_max3_f32 v153, v153, v154, v144
	v_max3_f32 v155, v155, v156, v145
	v_max3_f32 v153, v153, v155, v146
	v_max_f32_e32 v153, v153, v147
	v_cmp_lt_f32_e32 vcc, 0x41000000, v153
	s_cbranch_vccnz .Lgqa_rare0_gb
; DEVI unsigned pack2(float a, float b) { f32x2_t v = {a, b}; bf16x2_t r = __builtin_convertvector(v, bf16x2_t); return *reinterpret_cast<unsigned*>(&r); }
; DEVI float ex2(float x) { return __builtin_amdgcn_exp2f(x); }
; DEVI f32x4 mfma16(bf16x8 a, bf16x8 b, f32x4 c) { return __builtin_amdgcn_mfma_f32_16x16x32_bf16(a, b, c, 0, 0, 0); }
; template <int DK>
; DEVI void attn_tile(const char* kb, const char* vb, const bool first, const bf16x8 (&qf)[2][DK / 32], f32x4 (&o)[2][4],
;                     float (&mrun)[2], float (&lsum)[2], const int l15, const int quad) {
;     ...
;     float ps = 0.f;
; #pragma unroll
;     for (int ks = 0; ks < 4; ++ks)
; #pragma unroll
;       for (int j = 0; j < 4; ++j) { float pv = ex2(s[qt][ks][j]); s[qt][ks][j] = pv; ps += pv; }
;     lsum[qt] += ps;
; #pragma unroll
;     for (int k2 = 0; k2 < 2; ++k2) {
;       u32x4 wv;
;       wv[0] = pack2(s[qt][2 * k2][0], s[qt][2 * k2][1]);
;       wv[1] = pack2(s[qt][2 * k2][2], s[qt][2 * k2][3]);
;       wv[2] = pack2(s[qt][2 * k2 + 1][0], s[qt][2 * k2 + 1][1]);
;       wv[3] = pack2(s[qt][2 * k2 + 1][2], s[qt][2 * k2 + 1][3]);
;       pf[qt][k2] = as_bf8(wv);
;     }
;   }
; #pragma unroll
;   for (int dd = 0; dd < 4; ++dd)
; #pragma unroll
;     for (int k2 = 0; k2 < 2; ++k2) {
;       u32x2 lo = *reinterpret_cast<const u32x2*>(vb + (dd * 16 + l15) * 144 + (k2 * 32 + quad * 4) * 2);
;       u32x2 hi = *reinterpret_cast<const u32x2*>(vb + (dd * 16 + l15) * 144 + (k2 * 32 + 16 + quad * 4) * 2);
;       u32x4 vv = {lo[0], lo[1], hi[0], hi[1]};
;       bf16x8 vf = as_bf8(vv);
;       o[0][dd] = mfma16(vf, pf[0][k2], o[0][dd]);
;       o[1][dd] = mfma16(vf, pf[1][k2], o[1][dd]);
;     }
; template <int DK, int QP>
; DEVI void attn_item(const bf* __restrict__ Q, const bf* __restrict__ Kp, const bf* __restrict__ Vt, bf* __restrict__ outp  ,
;                     long row_base, int j0, int nkeys, char* smem) {
;     ...
;     AWRITE(rkA, rvA, (t + 1) & 1);
;     __syncthreads();
.Lgqa_join0_gb:
	v_add_u32_e32 v208, s18, v169
	ds_read_b64 v[100:101], v208 offset:0
	ds_read_b64 v[102:103], v208 offset:32
	ds_read_b64 v[104:105], v208 offset:2304
	ds_read_b64 v[106:107], v208 offset:2336
	ds_read_b64 v[108:109], v208 offset:4608
	ds_read_b64 v[110:111], v208 offset:4640
	ds_read_b64 v[112:113], v208 offset:6912
	ds_read_b64 v[114:115], v208 offset:6944
	v_mfma_f32_16x16x32_bf16 v[220:223], v[116:119], v[28:31], v[236:239]
	v_exp_f32_e32 v132, v132
	v_exp_f32_e32 v133, v133
	v_exp_f32_e32 v134, v134
	v_exp_f32_e32 v135, v135
	v_add_f32_e32 v154, v132, v133
	v_exp_f32_e32 v136, v136
	v_add_f32_e32 v155, v134, v135
	v_exp_f32_e32 v137, v137
	v_exp_f32_e32 v138, v138
	v_add_f32_e32 v154, v154, v136
	v_mfma_f32_16x16x32_bf16 v[220:223], v[120:123], v[32:35], v[220:223]
	v_exp_f32_e32 v139, v139
	v_add_f32_e32 v155, v155, v137
	v_exp_f32_e32 v140, v140
	v_add_f32_e32 v154, v154, v138
	v_exp_f32_e32 v141, v141
	v_add_f32_e32 v155, v155, v139
	v_exp_f32_e32 v142, v142
	v_add_f32_e32 v154, v154, v140
	v_exp_f32_e32 v143, v143
	v_add_f32_e32 v155, v155, v141
	v_mfma_f32_16x16x32_bf16 v[224:227], v[124:127], v[28:31], v[236:239]
	v_exp_f32_e32 v144, v144
	v_add_f32_e32 v154, v154, v142
	v_exp_f32_e32 v145, v145
	v_add_f32_e32 v155, v155, v143
	v_exp_f32_e32 v146, v146
	v_add_f32_e32 v154, v154, v144
	v_exp_f32_e32 v147, v147
	v_add_f32_e32 v155, v155, v145
	v_add_f32_e32 v154, v154, v146
	v_add_f32_e32 v155, v155, v147
	v_mfma_f32_16x16x32_bf16 v[224:227], v[128:131], v[32:35], v[224:227]
	v_add_f32_e32 v154, v154, v155
	v_add_f32_e32 v174, v174, v154
	v_cvt_pk_bf16_f32 v228, v132, v133
	v_cvt_pk_bf16_f32 v229, v134, v135
	v_cvt_pk_bf16_f32 v230, v136, v137
	v_cvt_pk_bf16_f32 v231, v138, v139
	v_cvt_pk_bf16_f32 v232, v140, v141
	v_cvt_pk_bf16_f32 v233, v142, v143
	v_cvt_pk_bf16_f32 v234, v144, v145
	v_cvt_pk_bf16_f32 v235, v146, v147
	ds_read_b64 v[116:117], v208 offset:64
	ds_read_b64 v[118:119], v208 offset:96
	ds_read_b64 v[120:121], v208 offset:2368
	ds_read_b64 v[122:123], v208 offset:2400
	ds_read_b64 v[124:125], v208 offset:4672
	ds_read_b64 v[126:127], v208 offset:4704
	ds_read_b64 v[128:129], v208 offset:6976
	ds_read_b64 v[130:131], v208 offset:7008
	v_max3_f32 v153, v212, v213, v214
	v_max3_f32 v154, v215, v216, v217
	v_max3_f32 v155, v218, v219, v220
	v_max3_f32 v156, v221, v222, v223
	s_waitcnt lgkmcnt(12)
	v_mfma_f32_16x16x32_bf16 v[72:75], v[100:103], v[228:231], v[72:75]
	v_max3_f32 v153, v153, v154, v224
	v_max3_f32 v155, v155, v156, v225
	v_mfma_f32_16x16x32_bf16 v[80:83], v[104:107], v[228:231], v[80:83]
	v_max3_f32 v153, v153, v155, v226
	v_max_f32_e32 v153, v153, v227
	v_cmp_lt_f32_e32 vcc, 0x41000000, v153
	s_cbranch_vccnz .Lgqa_rare1_gb
.Lgqa_join1_gb:
	s_waitcnt lgkmcnt(8)
	v_mfma_f32_16x16x32_bf16 v[88:91], v[108:111], v[228:231], v[88:91]
	v_exp_f32_e32 v212, v212
	v_exp_f32_e32 v213, v213
	v_exp_f32_e32 v214, v214
	v_exp_f32_e32 v215, v215
	v_add_f32_e32 v154, v212, v213
	v_exp_f32_e32 v216, v216
	v_mfma_f32_16x16x32_bf16 v[96:99], v[112:115], v[228:231], v[96:99]
	v_add_f32_e32 v155, v214, v215
	v_exp_f32_e32 v217, v217
	v_exp_f32_e32 v218, v218
	v_add_f32_e32 v154, v154, v216
	v_exp_f32_e32 v219, v219
	v_add_f32_e32 v155, v155, v217
	v_exp_f32_e32 v220, v220
	s_waitcnt lgkmcnt(4)
	v_mfma_f32_16x16x32_bf16 v[72:75], v[116:119], v[232:235], v[72:75]
	v_add_f32_e32 v154, v154, v218
	v_exp_f32_e32 v221, v221
	v_add_f32_e32 v155, v155, v219
	v_exp_f32_e32 v222, v222
	v_add_f32_e32 v154, v154, v220
	v_exp_f32_e32 v223, v223
	v_add_f32_e32 v155, v155, v221
	v_mfma_f32_16x16x32_bf16 v[80:83], v[120:123], v[232:235], v[80:83]
	v_exp_f32_e32 v224, v224
	v_add_f32_e32 v154, v154, v222
	v_exp_f32_e32 v225, v225
	v_add_f32_e32 v155, v155, v223
	v_exp_f32_e32 v226, v226
	v_add_f32_e32 v154, v154, v224
	s_waitcnt lgkmcnt(0)
	v_mfma_f32_16x16x32_bf16 v[88:91], v[124:127], v[232:235], v[88:91]
	v_exp_f32_e32 v227, v227
	v_add_f32_e32 v155, v155, v225
	v_add_f32_e32 v154, v154, v226
	v_add_f32_e32 v155, v155, v227
	v_add_f32_e32 v154, v154, v155
	v_add_f32_e32 v210, v210, v154
	v_cvt_pk_bf16_f32 v236, v212, v213
	v_mfma_f32_16x16x32_bf16 v[96:99], v[128:131], v[232:235], v[96:99]
	v_cvt_pk_bf16_f32 v237, v214, v215
	v_cvt_pk_bf16_f32 v238, v216, v217
	v_cvt_pk_bf16_f32 v239, v218, v219
	v_cvt_pk_bf16_f32 v240, v220, v221
	v_cvt_pk_bf16_f32 v241, v222, v223
	v_cvt_pk_bf16_f32 v242, v224, v225
	v_cvt_pk_bf16_f32 v243, v226, v227
	s_nop 0
	v_mfma_f32_16x16x32_bf16 v[68:71], v[100:103], v[236:239], v[68:71]
	v_mfma_f32_16x16x32_bf16 v[76:79], v[104:107], v[236:239], v[76:79]
	s_xor_b32 s18, s18, 0x4c00
	v_xor_b32_e32 v228, 0x80000000, v159
	v_mov_b32_e32 v229, v228
	v_mfma_f32_16x16x32_bf16 v[84:87], v[108:111], v[236:239], v[84:87]
	v_mov_b32_e32 v230, v228
	v_mov_b32_e32 v231, v228
	v_mfma_f32_16x16x32_bf16 v[92:95], v[112:115], v[236:239], v[92:95]
	v_add_u32_e32 v209, s18, v170
	v_add_u32_e32 v208, s18, v171
	v_mfma_f32_16x16x32_bf16 v[68:71], v[116:119], v[240:243], v[68:71]
	v_mfma_f32_16x16x32_bf16 v[76:79], v[120:123], v[240:243], v[76:79]
	s_waitcnt vmcnt(2)
	ds_write_b128 v209, v[192:195]
	ds_write_b128 v208, v[196:199]
	v_mfma_f32_16x16x32_bf16 v[84:87], v[124:127], v[240:243], v[84:87]
	v_add_u32_e32 v209, s18, v177
	v_mfma_f32_16x16x32_bf16 v[92:95], v[128:131], v[240:243], v[92:95]
	s_waitcnt vmcnt(0)
	ds_write_b128 v209, v[244:247] offset:10240
	ds_write_b128 v209, v[164:167] offset:14848
	v_xor_b32_e32 v236, 0x80000000, v157
	v_mov_b32_e32 v237, v236
	v_mov_b32_e32 v238, v236
	v_mov_b32_e32 v239, v236
	s_add_i32 s11, s11, 1
	s_cmp_lg_u32 s11, s3
	s_waitcnt lgkmcnt(0)
	s_barrier
	s_cbranch_scc1 .Lgqa_loop_g
	s_branch .Lgqa_exit_g

; template <int DK, int QP>
; DEVI void attn_item(const bf* __restrict__ Q, const bf* __restrict__ Kp, const bf* __restrict__ Vt, bf* __restrict__ outp  ,
;                     long row_base, int j0, int nkeys, char* smem) {
;     ...
;   for (int t = 0; t < nt; ++t) {
;     ALOAD(rkA, rvA, min(t + 1, nt - 1));
;     const char* kb = smem + (t & 1) * STG;
; #pragma unroll
;     for (int pr = 0; pr < QP; ++pr) {
;       attn_tile<DK>(kb, kb + KSZ, t == 0, qf[pr], o[pr], mrun[pr], lsum[pr], l15, quad);
;       if (QP > 1) __builtin_amdgcn_sched_barrier(0);
;     }
;     AWRITE(rkA, rvA, (t + 1) & 1);
;     __syncthreads();
;   }
.LBB0_633:
	v_exp_f32_e32 v112, v88
	v_exp_f32_e32 v113, v89
	v_exp_f32_e32 v114, v90
	v_exp_f32_e32 v115, v91
	v_exp_f32_e32 v116, v92
	v_exp_f32_e32 v117, v93
	v_exp_f32_e32 v118, v94
	v_exp_f32_e32 v119, v95
	v_exp_f32_e32 v120, v80
	v_exp_f32_e32 v121, v81
	v_exp_f32_e32 v122, v82
	v_exp_f32_e32 v123, v83
	v_exp_f32_e32 v136, v84
	v_exp_f32_e32 v137, v85
	v_exp_f32_e32 v138, v86
	v_exp_f32_e32 v139, v87
	v_exp_f32_e32 v108, v108
	v_exp_f32_e32 v109, v109
	v_exp_f32_e32 v110, v110
	v_exp_f32_e32 v111, v111
	v_exp_f32_e32 v104, v104
	v_exp_f32_e32 v105, v105
	v_exp_f32_e32 v106, v106
	v_exp_f32_e32 v107, v107
	v_cvt_pk_bf16_f32 v92, v112, v113
	v_cvt_pk_bf16_f32 v93, v114, v115
	v_cvt_pk_bf16_f32 v94, v116, v117
	v_cvt_pk_bf16_f32 v95, v118, v119
	v_exp_f32_e32 v140, v96
	v_exp_f32_e32 v141, v97
	s_waitcnt lgkmcnt(7)
	v_mfma_f32_16x16x32_bf16 v[84:87], v[56:59], v[92:95], 0
	v_exp_f32_e32 v142, v98
	v_exp_f32_e32 v143, v99
	v_exp_f32_e32 v144, v100
	v_exp_f32_e32 v145, v101
	v_cvt_pk_bf16_f32 v80, v120, v121
	v_cvt_pk_bf16_f32 v81, v122, v123
	v_cvt_pk_bf16_f32 v82, v136, v137
	v_cvt_pk_bf16_f32 v83, v138, v139
	v_exp_f32_e32 v146, v102
	v_exp_f32_e32 v147, v103
	v_cvt_pk_bf16_f32 v88, v108, v109
	v_cvt_pk_bf16_f32 v89, v110, v111
	v_cvt_pk_bf16_f32 v90, v104, v105
	v_cvt_pk_bf16_f32 v91, v106, v107
	v_mfma_f32_16x16x32_bf16 v[96:99], v[56:59], v[80:83], 0
	v_cvt_pk_bf16_f32 v100, v140, v141
	v_cvt_pk_bf16_f32 v101, v142, v143
	v_cvt_pk_bf16_f32 v102, v144, v145
	s_waitcnt lgkmcnt(6)
	v_mfma_f32_16x16x32_bf16 v[56:59], v[32:35], v[88:91], v[84:87]
	v_cvt_pk_bf16_f32 v103, v146, v147
	s_waitcnt vmcnt(4)
	ds_write_b128 v132, v[60:63] offset:23552
	s_waitcnt vmcnt(3)
	ds_write_b128 v133, v[64:67] offset:23552
	s_waitcnt vmcnt(2)
	ds_write_b128 v134, v[68:71] offset:23552
	s_waitcnt vmcnt(1)
	ds_write_b128 v135, v[72:75] offset:37888
	s_waitcnt vmcnt(0)
	ds_write_b128 v135, v[76:79] offset:42496
	v_add_f32_e32 v60, 0, v120
	s_waitcnt lgkmcnt(10)
	v_mfma_f32_16x16x32_bf16 v[84:87], v[48:51], v[92:95], 0
	v_add_f32_e32 v60, v121, v60
	v_add_f32_e32 v60, v122, v60
	v_add_f32_e32 v60, v123, v60
	v_mfma_f32_16x16x32_bf16 v[32:35], v[32:35], v[100:103], v[96:99]
	v_add_f32_e32 v60, v136, v60
	v_add_f32_e32 v60, v137, v60
	v_add_f32_e32 v60, v138, v60
	v_mfma_f32_16x16x32_bf16 v[96:99], v[48:51], v[80:83], 0
	v_add_f32_e32 v60, v139, v60
	v_add_f32_e32 v60, v140, v60
	v_add_f32_e32 v60, v141, v60
	s_waitcnt lgkmcnt(9)
	v_mfma_f32_16x16x32_bf16 v[48:51], v[28:31], v[88:91], v[84:87]
	v_add_f32_e32 v60, v142, v60
	v_add_f32_e32 v60, v143, v60
	s_mov_b32 s17, 0x8200
	v_add_f32_e32 v84, 0, v112
	v_add_f32_e32 v84, v113, v84
	v_add_f32_e32 v84, v114, v84
	v_mfma_f32_16x16x32_bf16 v[28:31], v[28:31], v[100:103], v[96:99]
	v_add_f32_e32 v60, v144, v60
	v_mad_i64_i32 v[168:169], s[10:11], v130, s17, 0
	s_nop 0
	v_add_f32_e32 v96, v115, v84
	v_add_f32_e32 v96, v116, v96
	v_add_f32_e32 v96, v117, v96
	s_waitcnt lgkmcnt(8)
	v_mfma_f32_16x16x32_bf16 v[84:87], v[44:47], v[92:95], 0
	v_add_f32_e32 v112, v118, v96
	v_mad_i64_i32 v[170:171], s[10:11], v131, s17, 0
	v_mfma_f32_16x16x32_bf16 v[96:99], v[44:47], v[80:83], 0
	v_add_f32_e32 v44, v119, v112
	v_add_f32_e32 v44, v108, v44
	v_add_f32_e32 v108, v109, v44
	s_waitcnt lgkmcnt(7)
	v_mfma_f32_16x16x32_bf16 v[44:47], v[36:39], v[88:91], v[84:87]
	v_add_f32_e32 v60, v145, v60
	s_movk_i32 s11, 0x90
	v_add_f32_e32 v60, v146, v60
	v_add_f32_e32 v84, v110, v108
	v_add_f32_e32 v84, v111, v84
	v_add_f32_e32 v84, v104, v84
	v_add_f32_e32 v84, v105, v84
	v_add_f32_e32 v84, v106, v84
	v_mfma_f32_16x16x32_bf16 v[36:39], v[36:39], v[100:103], v[96:99]
	v_add_f32_e32 v60, v147, v60
	s_add_i32 s10, s24, -1
	v_add_u32_e32 v209, 0xe00, v208
	v_add_f32_e32 v96, v107, v84
	s_waitcnt lgkmcnt(6)
	v_mfma_f32_16x16x32_bf16 v[84:87], v[52:55], v[92:95], 0
	v_add_f32_e32 v166, 0, v96
	v_add_u32_e32 v210, 0x1c00, v208
	v_add_u32_e32 v211, 0x2a00, v208
	v_mfma_f32_16x16x32_bf16 v[80:83], v[52:55], v[80:83], 0
	v_mul_u32_u24_e32 v212, 0x90, v158
	v_mad_u32_u24 v213, v158, s11, v191
	v_add_f32_e32 v153, 0, v60
	s_waitcnt lgkmcnt(5)
	v_mfma_f32_16x16x32_bf16 v[52:55], v[40:43], v[88:91], v[84:87]
	v_lshl_add_u64 v[172:173], v[124:125], 1, s[12:13]
	v_lshl_add_u64 v[174:175], v[126:127], 1, s[12:13]
	v_lshl_add_u64 v[176:177], v[128:129], 1, s[12:13]
	v_mfma_f32_16x16x32_bf16 v[40:43], v[40:43], v[100:103], v[80:83]
	v_mov_b32_e32 v84, 0x1200
	v_mad_u32_u24 v214, v158, s11, v84
	v_mov_b32_e32 v84, 0x1b00
	v_mad_u32_u24 v215, v158, s11, v84
	s_mov_b32 s11, 1
	s_waitcnt lgkmcnt(0)
	s_barrier
	v_add_u32_e32 v209, v208, v2
	v_mul_u32_u24_e32 v210, 0x90, v158
	v_add_u32_e32 v210, v210, v156
	v_add_u32_e32 v210, 0x3800, v210
	v_add_u32_e32 v155, v161, v165
	v_add_u32_e32 v157, v167, v204
	v_add_u32_e32 v159, v205, v206
	v_add_u32_e32 v165, v160, v207
	v_add_u32_e32 v174, v160, v168
	v_add_u32_e32 v175, v160, v170
	v_lshlrev_b32_e32 v167, 4, v178
	v_readfirstlane_b32 s22, v162
	v_readfirstlane_b32 s23, v163
	v_add_u32_e32 v172, 0x1000, v167
	v_add_u32_e32 v173, 0x2000, v167
	s_add_u32 s12, s12, 0x6000
	s_addc_u32 s13, s13, 0
	s_add_u32 s22, s22, 0x100
	s_addc_u32 s23, s23, 0
	s_mov_b32 s18, 0x5c00
	v_xor_b32_e32 v204, 0x80000000, v164
	v_mov_b32_e32 v205, v204
	v_mov_b32_e32 v206, v204
	v_mov_b32_e32 v207, v204
	v_xor_b32_e32 v212, 0x80000000, v1
	v_mov_b32_e32 v213, v212
	v_mov_b32_e32 v214, v212
	v_mov_b32_e32 v215, v212
	s_nop 4
; template <int DK>
; DEVI void attn_tile(const char* kb, const char* vb, const bool first, const bf16x8 (&qf)[2][DK / 32], f32x4 (&o)[2][4],
;                     float (&mrun)[2], float (&lsum)[2], const int l15, const int quad) {
;     ...
; #pragma unroll
;   for (int ks = 0; ks < 4; ++ks)
; #pragma unroll
;     for (int kk = 0; kk < NKK; ++kk) {
;       bf16x8 kf = *reinterpret_cast<const bf16x8*>(kb + (ks * 16 + l15) * KSTR + (kk * 32 + quad * 8) * 2);
;       s[0][ks] = mfma16(kf, qf[0][kk], s[0][ks]);
;       s[1][ks] = mfma16(kf, qf[1][kk], s[1][ks]);
;     }
;   bf16x8 pf[2][2];
; #pragma unroll
;   for (int qt = 0; qt < 2; ++qt) {
;     float mx = fmaxf(fmaxf(s[qt][0][0], s[qt][0][1]), fmaxf(s[qt][0][2], s[qt][0][3]));
; #pragma unroll
;     for (int ks = 1; ks < 4; ++ks) mx = fmaxf(mx, fmaxf(fmaxf(s[qt][ks][0], s[qt][ks][1]), fmaxf(s[qt][ks][2], s[qt][ks][3])));
;     if (__any(first || (mx > 8.f))) {
;       float rm = fmaxf(mx, __shfl_xor(mx, 16));
;       rm = fmaxf(rm, __shfl_xor(rm, 32));
;       const float delta = first ? rm : fmaxf(rm, 0.f);
;       const float alpha = first ? 1.f : ex2(-delta);
;       mrun[qt] += delta;
;       lsum[qt] *= alpha;
; #pragma unroll
;       for (int ks = 0; ks < 4; ++ks)
; #pragma unroll
;         for (int j = 0; j < 4; ++j) s[qt][ks][j] -= delta;
; #pragma unroll
;       for (int dd = 0; dd < 4; ++dd)
; #pragma unroll
;         for (int j = 0; j < 4; ++j) o[qt][dd][j] *= alpha;
;     }
;     float ps = 0.f;
; #pragma unroll
;     for (int ks = 0; ks < 4; ++ks)
; #pragma unroll
;       for (int j = 0; j < 4; ++j) { float pv = ex2(s[qt][ks][j]); s[qt][ks][j] = pv; ps += pv; }
;     lsum[qt] += ps;
; #pragma unroll
;     for (int k2 = 0; k2 < 2; ++k2) {
;       u32x4 wv;
;       wv[0] = pack2(s[qt][2 * k2][0], s[qt][2 * k2][1]);
;       wv[1] = pack2(s[qt][2 * k2][2], s[qt][2 * k2][3]);
;       wv[2] = pack2(s[qt][2 * k2 + 1][0], s[qt][2 * k2 + 1][1]);
;       wv[3] = pack2(s[qt][2 * k2 + 1][2], s[qt][2 * k2 + 1][3]);
;       pf[qt][k2] = as_bf8(wv);
;     }
;   }
; #pragma unroll
;   for (int dd = 0; dd < 4; ++dd)
; #pragma unroll
;     for (int k2 = 0; k2 < 2; ++k2) {
;       u32x2 lo = *reinterpret_cast<const u32x2*>(vb + (dd * 16 + l15) * 144 + (k2 * 32 + quad * 4) * 2);
;       u32x2 hi = *reinterpret_cast<const u32x2*>(vb + (dd * 16 + l15) * 144 + (k2 * 32 + 16 + quad * 4) * 2);
.Lmla_loop_a:
	v_add_u32_e32 v148, s18, v209
	global_load_dwordx4 v[224:227], v167, s[12:13]
	global_load_dwordx4 v[228:231], v172, s[12:13]
	global_load_dwordx4 v[232:235], v173, s[12:13]
	ds_read_b128 v[60:63], v148
	ds_read_b128 v[64:67], v148 offset:64
	ds_read_b128 v[68:71], v148 offset:128
	global_load_dwordx4 v[168:171], v174, s[22:23]
	global_load_dwordx4 v[160:163], v175, s[22:23]
	ds_read_b128 v[72:75], v148 offset:3584
	ds_read_b128 v[76:79], v148 offset:3648
	ds_read_b128 v[80:83], v148 offset:3712
	ds_read_b128 v[84:87], v148 offset:7168
	ds_read_b128 v[88:91], v148 offset:7232
	ds_read_b128 v[92:95], v148 offset:7296
	ds_read_b128 v[96:99], v148 offset:10752
	ds_read_b128 v[100:103], v148 offset:10816
	ds_read_b128 v[104:107], v148 offset:10880
	s_add_i32 s96, s11, 2
	s_cmp_lt_i32 s96, s24
	s_cselect_b32 s96, 0x3000, 0
	s_cselect_b32 s17, 0x80, 0
	s_add_u32 s12, s12, s96
	s_addc_u32 s13, s13, 0
	s_add_u32 s22, s22, s17
	s_addc_u32 s23, s23, 0
	s_waitcnt lgkmcnt(11)
	v_mfma_f32_16x16x32_bf16 v[108:111], v[60:63], v[4:7], v[204:207]
	s_waitcnt lgkmcnt(9)
	v_mfma_f32_16x16x32_bf16 v[108:111], v[64:67], v[8:11], v[108:111]
	v_mfma_f32_16x16x32_bf16 v[108:111], v[68:71], v[12:15], v[108:111]
	s_waitcnt lgkmcnt(6)
	v_mfma_f32_16x16x32_bf16 v[112:115], v[72:75], v[4:7], v[204:207]
	v_mfma_f32_16x16x32_bf16 v[112:115], v[76:79], v[8:11], v[112:115]
	v_mfma_f32_16x16x32_bf16 v[112:115], v[80:83], v[12:15], v[112:115]
	s_waitcnt lgkmcnt(3)
	v_mfma_f32_16x16x32_bf16 v[116:119], v[84:87], v[4:7], v[204:207]
	v_mfma_f32_16x16x32_bf16 v[116:119], v[88:91], v[8:11], v[116:119]
	v_mfma_f32_16x16x32_bf16 v[116:119], v[92:95], v[12:15], v[116:119]
	s_waitcnt lgkmcnt(0)
	v_mfma_f32_16x16x32_bf16 v[120:123], v[96:99], v[4:7], v[204:207]
	v_mfma_f32_16x16x32_bf16 v[120:123], v[100:103], v[8:11], v[120:123]
	v_mfma_f32_16x16x32_bf16 v[120:123], v[104:107], v[12:15], v[120:123]
	v_mfma_f32_16x16x32_bf16 v[124:127], v[60:63], v[16:19], v[212:215]
	v_mfma_f32_16x16x32_bf16 v[124:127], v[64:67], v[20:23], v[124:127]
	v_max3_f32 v150, v108, v109, v110
	v_max3_f32 v151, v111, v112, v113
	v_mfma_f32_16x16x32_bf16 v[124:127], v[68:71], v[24:27], v[124:127]
	v_max3_f32 v176, v114, v115, v116
	v_max3_f32 v177, v117, v118, v119
	v_mfma_f32_16x16x32_bf16 v[128:131], v[72:75], v[16:19], v[212:215]
	s_nop 0
	v_max3_f32 v150, v150, v151, v120
	v_max3_f32 v176, v176, v177, v121
	v_mfma_f32_16x16x32_bf16 v[128:131], v[76:79], v[20:23], v[128:131]
	v_max3_f32 v150, v150, v176, v122
	v_max_f32_e32 v150, v150, v123
	v_cmp_lt_f32_e32 vcc, 0x41000000, v150
	s_cbranch_vccnz .Lmla_rare0_a
.Lmla_join0_a:
	v_mfma_f32_16x16x32_bf16 v[128:131], v[80:83], v[24:27], v[128:131]
	v_add_u32_e32 v149, s18, v210
	ds_read_b64 v[60:61], v149 offset:0
	ds_read_b64 v[62:63], v149 offset:32
	ds_read_b64 v[64:65], v149 offset:2304
	ds_read_b64 v[66:67], v149 offset:2336
	ds_read_b64 v[68:69], v149 offset:4608
	ds_read_b64 v[70:71], v149 offset:4640
	ds_read_b64 v[72:73], v149 offset:6912
	ds_read_b64 v[74:75], v149 offset:6944
	v_exp_f32_e32 v108, v108
	v_exp_f32_e32 v109, v109
	v_exp_f32_e32 v110, v110
	v_exp_f32_e32 v111, v111
	v_add_f32_e32 v151, v108, v109
	v_mfma_f32_16x16x32_bf16 v[132:135], v[84:87], v[16:19], v[212:215]
	v_exp_f32_e32 v112, v112
	v_add_f32_e32 v176, v110, v111
	v_exp_f32_e32 v113, v113
	v_exp_f32_e32 v114, v114
	v_add_f32_e32 v151, v151, v112
	v_exp_f32_e32 v115, v115
	v_mfma_f32_16x16x32_bf16 v[132:135], v[88:91], v[20:23], v[132:135]
	v_add_f32_e32 v176, v176, v113
	v_exp_f32_e32 v116, v116
	v_add_f32_e32 v151, v151, v114
	v_exp_f32_e32 v117, v117
	v_add_f32_e32 v176, v176, v115
	v_exp_f32_e32 v118, v118
	ds_read_b64 v[76:77], v149 offset:64
	ds_read_b64 v[78:79], v149 offset:96
	ds_read_b64 v[80:81], v149 offset:2368
	ds_read_b64 v[82:83], v149 offset:2400
	ds_read_b64 v[84:85], v149 offset:4672
	ds_read_b64 v[86:87], v149 offset:4704
	ds_read_b64 v[88:89], v149 offset:6976
	ds_read_b64 v[90:91], v149 offset:7008
	v_mfma_f32_16x16x32_bf16 v[132:135], v[92:95], v[24:27], v[132:135]
	v_add_f32_e32 v151, v151, v116
	v_exp_f32_e32 v119, v119
	v_add_f32_e32 v176, v176, v117
	v_exp_f32_e32 v120, v120
	v_add_f32_e32 v151, v151, v118
	v_mfma_f32_16x16x32_bf16 v[136:139], v[96:99], v[16:19], v[212:215]
	v_exp_f32_e32 v121, v121
	v_add_f32_e32 v176, v176, v119
	v_exp_f32_e32 v122, v122
	v_add_f32_e32 v151, v151, v120
	v_exp_f32_e32 v123, v123
	v_add_f32_e32 v176, v176, v121
	v_mfma_f32_16x16x32_bf16 v[136:139], v[100:103], v[20:23], v[136:139]
	v_add_f32_e32 v151, v151, v122
	v_add_f32_e32 v176, v176, v123
	v_add_f32_e32 v151, v151, v176
	v_add_f32_e32 v166, v166, v151
	v_cvt_pk_bf16_f32 v140, v108, v109
	v_cvt_pk_bf16_f32 v141, v110, v111
	v_mfma_f32_16x16x32_bf16 v[136:139], v[104:107], v[24:27], v[136:139]
	v_cvt_pk_bf16_f32 v142, v112, v113
	v_cvt_pk_bf16_f32 v143, v114, v115
	v_cvt_pk_bf16_f32 v144, v116, v117
	v_cvt_pk_bf16_f32 v145, v118, v119
	v_cvt_pk_bf16_f32 v146, v120, v121
	v_cvt_pk_bf16_f32 v147, v122, v123
	s_waitcnt lgkmcnt(12)
	v_mfma_f32_16x16x32_bf16 v[56:59], v[60:63], v[140:143], v[56:59]
	v_max3_f32 v150, v124, v125, v126
	v_max3_f32 v151, v127, v128, v129
	v_mfma_f32_16x16x32_bf16 v[48:51], v[64:67], v[140:143], v[48:51]
	v_max3_f32 v176, v130, v131, v132
	v_max3_f32 v177, v133, v134, v135
	v_max3_f32 v150, v150, v151, v136
	v_max3_f32 v176, v176, v177, v137
	s_waitcnt lgkmcnt(8)
	v_mfma_f32_16x16x32_bf16 v[44:47], v[68:71], v[140:143], v[44:47]
	v_max3_f32 v150, v150, v176, v138
	v_max_f32_e32 v150, v150, v139
	v_cmp_lt_f32_e32 vcc, 0x41000000, v150
	s_cbranch_vccnz .Lmla_rare1_a
; DEVI unsigned pack2(float a, float b) { f32x2_t v = {a, b}; bf16x2_t r = __builtin_convertvector(v, bf16x2_t); return *reinterpret_cast<unsigned*>(&r); }
; template <int DK>
; DEVI void attn_tile(const char* kb, const char* vb, const bool first, const bf16x8 (&qf)[2][DK / 32], f32x4 (&o)[2][4],
;                     float (&mrun)[2], float (&lsum)[2], const int l15, const int quad) {
;     ...
;     if (__any(first || (mx > 8.f))) {
;       float rm = fmaxf(mx, __shfl_xor(mx, 16));
;       rm = fmaxf(rm, __shfl_xor(rm, 32));
;       const float delta = first ? rm : fmaxf(rm, 0.f);
;       const float alpha = first ? 1.f : ex2(-delta);
;       mrun[qt] += delta;
;       lsum[qt] *= alpha;
; #pragma unroll
;       for (int ks = 0; ks < 4; ++ks)
; #pragma unroll
;         for (int j = 0; j < 4; ++j) s[qt][ks][j] -= delta;
; #pragma unroll
;       for (int dd = 0; dd < 4; ++dd)
; #pragma unroll
;         for (int j = 0; j < 4; ++j) o[qt][dd][j] *= alpha;
;     }
;     float ps = 0.f;
; #pragma unroll
;     for (int ks = 0; ks < 4; ++ks)
; #pragma unroll
;       for (int j = 0; j < 4; ++j) { float pv = ex2(s[qt][ks][j]); s[qt][ks][j] = pv; ps += pv; }
;     lsum[qt] += ps;
; #pragma unroll
;     for (int k2 = 0; k2 < 2; ++k2) {
;       u32x4 wv;
;       wv[0] = pack2(s[qt][2 * k2][0], s[qt][2 * k2][1]);
;       wv[1] = pack2(s[qt][2 * k2][2], s[qt][2 * k2][3]);
;       wv[2] = pack2(s[qt][2 * k2 + 1][0], s[qt][2 * k2 + 1][1]);
;       wv[3] = pack2(s[qt][2 * k2 + 1][2], s[qt][2 * k2 + 1][3]);
;       pf[qt][k2] = as_bf8(wv);
;     }
;   }
; #pragma unroll
;   for (int dd = 0; dd < 4; ++dd)
; #pragma unroll
;     for (int k2 = 0; k2 < 2; ++k2) {
;       u32x2 lo = *reinterpret_cast<const u32x2*>(vb + (dd * 16 + l15) * 144 + (k2 * 32 + quad * 4) * 2);
;       u32x2 hi = *reinterpret_cast<const u32x2*>(vb + (dd * 16 + l15) * 144 + (k2 * 32 + 16 + quad * 4) * 2);
;       u32x4 vv = {lo[0], lo[1], hi[0], hi[1]};
;       bf16x8 vf = as_bf8(vv);
;       o[0][dd] = mfma16(vf, pf[0][k2], o[0][dd]);
;       o[1][dd] = mfma16(vf, pf[1][k2], o[1][dd]);
;     }
; template <int DK, int QP>
; DEVI void attn_item(const bf* __restrict__ Q, const bf* __restrict__ Kp, const bf* __restrict__ Vt, bf* __restrict__ outp  ,
;                     long row_base, int j0, int nkeys, char* smem) {
;     ...
;     AWRITE(rkA, rvA, (t + 1) & 1);
;     __syncthreads();
.Lmla_join1_a:
	v_mfma_f32_16x16x32_bf16 v[52:55], v[72:75], v[140:143], v[52:55]
	v_exp_f32_e32 v124, v124
	v_exp_f32_e32 v125, v125
	v_exp_f32_e32 v126, v126
	v_exp_f32_e32 v127, v127
	v_add_f32_e32 v151, v124, v125
	v_exp_f32_e32 v128, v128
	v_add_f32_e32 v176, v126, v127
	v_exp_f32_e32 v129, v129
	s_waitcnt lgkmcnt(4)
	v_mfma_f32_16x16x32_bf16 v[56:59], v[76:79], v[144:147], v[56:59]
	v_exp_f32_e32 v130, v130
	v_add_f32_e32 v151, v151, v128
	v_exp_f32_e32 v131, v131
	v_add_f32_e32 v176, v176, v129
	v_exp_f32_e32 v132, v132
	v_add_f32_e32 v151, v151, v130
	v_exp_f32_e32 v133, v133
	v_add_f32_e32 v176, v176, v131
	v_mfma_f32_16x16x32_bf16 v[48:51], v[80:83], v[144:147], v[48:51]
	v_exp_f32_e32 v134, v134
	v_add_f32_e32 v151, v151, v132
	v_exp_f32_e32 v135, v135
	v_add_f32_e32 v176, v176, v133
	v_exp_f32_e32 v136, v136
	v_add_f32_e32 v151, v151, v134
	v_exp_f32_e32 v137, v137
	v_add_f32_e32 v176, v176, v135
	s_waitcnt lgkmcnt(0)
	v_mfma_f32_16x16x32_bf16 v[44:47], v[84:87], v[144:147], v[44:47]
	v_exp_f32_e32 v138, v138
	v_add_f32_e32 v151, v151, v136
	v_exp_f32_e32 v139, v139
	v_add_f32_e32 v176, v176, v137
	v_add_f32_e32 v151, v151, v138
	v_add_f32_e32 v176, v176, v139
	v_add_f32_e32 v151, v151, v176
	v_add_f32_e32 v153, v153, v151
	v_mfma_f32_16x16x32_bf16 v[52:55], v[88:91], v[144:147], v[52:55]
	v_cvt_pk_bf16_f32 v216, v124, v125
	v_cvt_pk_bf16_f32 v217, v126, v127
	v_cvt_pk_bf16_f32 v218, v128, v129
	v_cvt_pk_bf16_f32 v219, v130, v131
	v_cvt_pk_bf16_f32 v220, v132, v133
	v_cvt_pk_bf16_f32 v221, v134, v135
	v_cvt_pk_bf16_f32 v222, v136, v137
	v_cvt_pk_bf16_f32 v223, v138, v139
	s_xor_b32 s18, s18, 0x5c00
	s_nop 0
	v_mfma_f32_16x16x32_bf16 v[32:35], v[60:63], v[216:219], v[32:35]
	v_mfma_f32_16x16x32_bf16 v[28:31], v[64:67], v[216:219], v[28:31]
	v_add_u32_e32 v150, s18, v155
	v_add_u32_e32 v151, s18, v157
	v_mfma_f32_16x16x32_bf16 v[36:39], v[68:71], v[216:219], v[36:39]
	v_mfma_f32_16x16x32_bf16 v[40:43], v[72:75], v[216:219], v[40:43]
	s_waitcnt vmcnt(2)
	ds_write_b128 v150, v[224:227]
	ds_write_b128 v151, v[228:231]
	v_mfma_f32_16x16x32_bf16 v[32:35], v[76:79], v[220:223], v[32:35]
	v_add_u32_e32 v150, s18, v159
	v_add_u32_e32 v151, s18, v165
	v_mfma_f32_16x16x32_bf16 v[28:31], v[80:83], v[220:223], v[28:31]
	v_mfma_f32_16x16x32_bf16 v[36:39], v[84:87], v[220:223], v[36:39]
	ds_write_b128 v150, v[232:235]
	v_mfma_f32_16x16x32_bf16 v[40:43], v[88:91], v[220:223], v[40:43]
	s_waitcnt vmcnt(0)
	ds_write_b128 v151, v[168:171] offset:14336
	ds_write_b128 v151, v[160:163] offset:18944
	s_add_i32 s11, s11, 1
	s_cmp_lg_u32 s11, s24
	s_waitcnt lgkmcnt(0)
	s_barrier
	s_cbranch_scc1 .Lmla_loop_a
	s_branch .Lmla_exit_a
.Lmla_rare0_a:
	v_cmp_lt_i32_e32 vcc, v186, v184
	s_nop 1
	v_cndmask_b32_e32 v151, v183, v186, vcc
	v_lshlrev_b32_e32 v151, 2, v151
	ds_bpermute_b32 v151, v151, v150
	v_cmp_lt_i32_e32 vcc, v185, v184
	s_waitcnt lgkmcnt(0)
	v_max_f32_e32 v150, v150, v151
	v_cndmask_b32_e32 v151, v183, v185, vcc
	v_lshlrev_b32_e32 v151, 2, v151
	ds_bpermute_b32 v151, v151, v150
	s_waitcnt lgkmcnt(0)
	v_max3_f32 v150, v150, v151, 0
	v_exp_f32_e64 v176, -v150
	v_add_f32_e32 v164, v164, v150
	v_sub_f32_e32 v204, v204, v150
	v_sub_f32_e32 v205, v205, v150
	v_sub_f32_e32 v206, v206, v150
	v_sub_f32_e32 v207, v207, v150
	v_sub_f32_e32 v108, v108, v150
	v_sub_f32_e32 v109, v109, v150
	v_sub_f32_e32 v110, v110, v150
	v_sub_f32_e32 v111, v111, v150
	v_sub_f32_e32 v112, v112, v150
	v_sub_f32_e32 v113, v113, v150
	v_sub_f32_e32 v114, v114, v150
	v_sub_f32_e32 v115, v115, v150
	v_sub_f32_e32 v116, v116, v150
	v_sub_f32_e32 v117, v117, v150
	v_sub_f32_e32 v118, v118, v150
	v_sub_f32_e32 v119, v119, v150
	v_sub_f32_e32 v120, v120, v150
	v_sub_f32_e32 v121, v121, v150
	v_sub_f32_e32 v122, v122, v150
	v_sub_f32_e32 v123, v123, v150
	v_mul_f32_e32 v166, v166, v176
	v_mul_f32_e32 v56, v56, v176
	v_mul_f32_e32 v57, v57, v176
	v_mul_f32_e32 v58, v58, v176
	v_mul_f32_e32 v59, v59, v176
	v_mul_f32_e32 v48, v48, v176
	v_mul_f32_e32 v49, v49, v176
	v_mul_f32_e32 v50, v50, v176
	v_mul_f32_e32 v51, v51, v176
	v_mul_f32_e32 v44, v44, v176
	v_mul_f32_e32 v45, v45, v176
	v_mul_f32_e32 v46, v46, v176
	v_mul_f32_e32 v47, v47, v176
	v_mul_f32_e32 v52, v52, v176
	v_mul_f32_e32 v53, v53, v176
	v_mul_f32_e32 v54, v54, v176
	v_mul_f32_e32 v55, v55, v176
	s_branch .Lmla_join0_a
.Lmla_rare1_a:
	v_cmp_lt_i32_e32 vcc, v186, v184
	s_nop 1
	v_cndmask_b32_e32 v151, v183, v186, vcc
	v_lshlrev_b32_e32 v151, 2, v151
	ds_bpermute_b32 v151, v151, v150
	v_cmp_lt_i32_e32 vcc, v185, v184
	s_waitcnt lgkmcnt(0)
	v_max_f32_e32 v150, v150, v151
	v_cndmask_b32_e32 v151, v183, v185, vcc
	v_lshlrev_b32_e32 v151, 2, v151
	ds_bpermute_b32 v151, v151, v150
	s_waitcnt lgkmcnt(0)
	v_max3_f32 v150, v150, v151, 0
	v_exp_f32_e64 v176, -v150
	v_add_f32_e32 v1, v1, v150
	v_sub_f32_e32 v212, v212, v150
	v_sub_f32_e32 v213, v213, v150
	v_sub_f32_e32 v214, v214, v150
	v_sub_f32_e32 v215, v215, v150
	v_sub_f32_e32 v124, v124, v150
	v_sub_f32_e32 v125, v125, v150
	v_sub_f32_e32 v126, v126, v150
	v_sub_f32_e32 v127, v127, v150
	v_sub_f32_e32 v128, v128, v150
	v_sub_f32_e32 v129, v129, v150
	v_sub_f32_e32 v130, v130, v150
	v_sub_f32_e32 v131, v131, v150
	v_sub_f32_e32 v132, v132, v150
	v_sub_f32_e32 v133, v133, v150
	v_sub_f32_e32 v134, v134, v150
	v_sub_f32_e32 v135, v135, v150
	v_sub_f32_e32 v136, v136, v150
	v_sub_f32_e32 v137, v137, v150
	v_sub_f32_e32 v138, v138, v150
	v_sub_f32_e32 v139, v139, v150
	v_mul_f32_e32 v153, v153, v176
	v_mul_f32_e32 v32, v32, v176
	v_mul_f32_e32 v33, v33, v176
	v_mul_f32_e32 v34, v34, v176
	v_mul_f32_e32 v35, v35, v176
	v_mul_f32_e32 v28, v28, v176
	v_mul_f32_e32 v29, v29, v176
	v_mul_f32_e32 v30, v30, v176
	v_mul_f32_e32 v31, v31, v176
	v_mul_f32_e32 v36, v36, v176
	v_mul_f32_e32 v37, v37, v176
	v_mul_f32_e32 v38, v38, v176
	v_mul_f32_e32 v39, v39, v176
	v_mul_f32_e32 v40, v40, v176
	v_mul_f32_e32 v41, v41, v176
	v_mul_f32_e32 v42, v42, v176
	v_mul_f32_e32 v43, v43, v176
	s_branch .Lmla_join1_a
